# s1 outputs: o_intra (4x8B->2x16B, permlane16_swap) and attention y_a (8x8B->4x16B, permlane32_swap) stores widened, write-through
# speedup vs baseline: 1.0003x; 1.0003x over previous
.LBB0_188:
	s_or_b64 exec, exec, s[4:5]
	v_lshlrev_b32_e32 v176, 1, v125
	v_lshl_add_u64 v[32:33], v[126:127], 0, v[176:177]
	global_load_dwordx2 v[46:47], v[32:33], off offset:1024
	global_load_dwordx2 v[44:45], v[32:33], off offset:1040
	global_load_dwordx2 v[42:43], v[32:33], off offset:1056
	global_load_dwordx2 v[40:41], v[32:33], off offset:1072
	global_load_dwordx2 v[38:39], v[32:33], off offset:1088
	global_load_dwordx2 v[36:37], v[32:33], off offset:1104
	global_load_dwordx2 v[34:35], v[32:33], off offset:1120
	s_nop 0
	global_load_dwordx2 v[32:33], v[32:33], off offset:1136
	v_readlane_b32 s2, v254, 13
	v_readlane_b32 s3, v254, 14
	v_mov_b32_e32 v125, v177
	s_waitcnt vmcnt(7)
	v_lshlrev_b32_e32 v50, 16, v46
	v_and_b32_e32 v51, 0xffff0000, v46
	v_mul_f32_e32 v46, 0xbfb8aa3b, v50
	v_exp_f32_e32 v46, v46
	v_mov_b64_e32 v[48:49], s[2:3]
	v_mad_i64_i32 v[48:49], s[2:3], v136, s67, v[48:49]
	v_add_f32_e32 v46, 1.0, v46
	v_rcp_f32_e32 v52, v46
	v_mul_f32_e32 v46, 0xbfb8aa3b, v51
	v_exp_f32_e32 v46, v46
	v_lshl_add_u64 v[48:49], v[48:49], 0, v[124:125]
	v_add_f32_e32 v46, 1.0, v46
	v_rcp_f32_e32 v53, v46
	s_nop 0
	v_pk_mul_f32 v[50:51], v[52:53], v[50:51]
	s_nop 0
	v_pk_mul_f32 v[16:17], v[16:17], v[50:51]
	s_nop 0
	v_cvt_pk_bf16_f32 v46, v16, v17
	v_lshlrev_b32_e32 v16, 16, v47
	v_and_b32_e32 v17, 0xffff0000, v47
	v_mul_f32_e32 v47, 0xbfb8aa3b, v16
	v_exp_f32_e32 v47, v47
	s_nop 0
	v_add_f32_e32 v47, 1.0, v47
	v_rcp_f32_e32 v50, v47
	v_mul_f32_e32 v47, 0xbfb8aa3b, v17
	v_exp_f32_e32 v47, v47
	s_nop 0
	v_add_f32_e32 v47, 1.0, v47
	v_rcp_f32_e32 v51, v47
	s_nop 0
	v_pk_mul_f32 v[16:17], v[50:51], v[16:17]
	s_nop 0
	v_pk_mul_f32 v[16:17], v[18:19], v[16:17]
	s_waitcnt vmcnt(6)
	v_lshlrev_b32_e32 v18, 16, v44
	v_and_b32_e32 v19, 0xffff0000, v44
	v_mul_f32_e32 v44, 0xbfb8aa3b, v18
	v_exp_f32_e32 v44, v44
	v_cvt_pk_bf16_f32 v47, v16, v17
	v_lshl_add_u64 v[16:17], v[48:49], 0, v[176:177]
	v_lshrrev_b32_e32 v104, 5, v210
	v_lshlrev_b32_e32 v104, 3, v104
	v_mov_b32_e32 v105, v177
	v_lshl_add_u64 v[104:105], v[16:17], 0, v[104:105]
	v_mov_b32_e32 v100, v46
	v_mov_b32_e32 v101, v47
	v_add_f32_e32 v44, 1.0, v44
	v_rcp_f32_e32 v46, v44
	v_mul_f32_e32 v44, 0xbfb8aa3b, v19
	v_exp_f32_e32 v44, v44
	s_nop 0
	v_add_f32_e32 v44, 1.0, v44
	v_rcp_f32_e32 v47, v44
	s_nop 0
	v_pk_mul_f32 v[18:19], v[46:47], v[18:19]
	s_nop 0
	v_pk_mul_f32 v[18:19], v[20:21], v[18:19]
	v_lshlrev_b32_e32 v20, 16, v45
	v_cvt_pk_bf16_f32 v18, v18, v19
	v_mul_f32_e32 v19, 0xbfb8aa3b, v20
	v_exp_f32_e32 v19, v19
	v_and_b32_e32 v21, 0xffff0000, v45
	v_add_f32_e32 v19, 1.0, v19
	v_rcp_f32_e32 v44, v19
	v_mul_f32_e32 v19, 0xbfb8aa3b, v21
	v_exp_f32_e32 v19, v19
	s_nop 0
	v_add_f32_e32 v19, 1.0, v19
	v_rcp_f32_e32 v45, v19
	s_nop 0
	v_pk_mul_f32 v[20:21], v[44:45], v[20:21]
	s_nop 0
	v_pk_mul_f32 v[20:21], v[22:23], v[20:21]
	s_nop 0
	v_cvt_pk_bf16_f32 v19, v20, v21
	v_mov_b32_e32 v102, v18
	v_mov_b32_e32 v103, v19
	s_nop 1
	v_permlane32_swap_b32_e32 v100, v102
	v_permlane32_swap_b32_e32 v101, v103
	s_nop 1
	global_store_dwordx4 v[104:105], v[100:103], off sc1
	s_waitcnt vmcnt(6)
	v_lshlrev_b32_e32 v18, 16, v42
	v_and_b32_e32 v19, 0xffff0000, v42
	v_mul_f32_e32 v20, 0xbfb8aa3b, v18
	v_mul_f32_e32 v21, 0xbfb8aa3b, v19
	v_exp_f32_e32 v20, v20
	v_exp_f32_e32 v21, v21
	v_add_f32_e32 v20, 1.0, v20
	v_add_f32_e32 v21, 1.0, v21
	v_rcp_f32_e32 v20, v20
	v_rcp_f32_e32 v21, v21
	s_nop 0
	v_pk_mul_f32 v[18:19], v[20:21], v[18:19]
	s_nop 0
	v_pk_mul_f32 v[18:19], v[24:25], v[18:19]
	v_lshlrev_b32_e32 v20, 16, v43
	v_cvt_pk_bf16_f32 v18, v18, v19
	v_mul_f32_e32 v19, 0xbfb8aa3b, v20
	v_exp_f32_e32 v19, v19
	v_and_b32_e32 v21, 0xffff0000, v43
	v_add_f32_e32 v19, 1.0, v19
	v_rcp_f32_e32 v22, v19
	v_mul_f32_e32 v19, 0xbfb8aa3b, v21
	v_exp_f32_e32 v19, v19
	s_nop 0
	v_add_f32_e32 v19, 1.0, v19
	v_rcp_f32_e32 v23, v19
	s_nop 0
	v_pk_mul_f32 v[20:21], v[22:23], v[20:21]
	s_nop 0
	v_pk_mul_f32 v[20:21], v[26:27], v[20:21]
	s_nop 0
	v_cvt_pk_bf16_f32 v19, v20, v21
	v_mov_b32_e32 v100, v18
	v_mov_b32_e32 v101, v19
	s_waitcnt vmcnt(5)
	v_lshlrev_b32_e32 v18, 16, v40
	v_and_b32_e32 v19, 0xffff0000, v40
	v_mul_f32_e32 v20, 0xbfb8aa3b, v18
	v_mul_f32_e32 v21, 0xbfb8aa3b, v19
	v_exp_f32_e32 v20, v20
	v_exp_f32_e32 v21, v21
	v_add_f32_e32 v20, 1.0, v20
	v_add_f32_e32 v21, 1.0, v21
	v_rcp_f32_e32 v20, v20
	v_rcp_f32_e32 v21, v21
	s_nop 0
	v_pk_mul_f32 v[18:19], v[20:21], v[18:19]
	s_nop 0
	v_pk_mul_f32 v[18:19], v[28:29], v[18:19]
	v_lshlrev_b32_e32 v20, 16, v41
	v_cvt_pk_bf16_f32 v18, v18, v19
	v_mul_f32_e32 v19, 0xbfb8aa3b, v20
	v_exp_f32_e32 v19, v19
	v_and_b32_e32 v21, 0xffff0000, v41
	v_add_f32_e32 v19, 1.0, v19
	v_rcp_f32_e32 v22, v19
	v_mul_f32_e32 v19, 0xbfb8aa3b, v21
	v_exp_f32_e32 v19, v19
	s_nop 0
	v_add_f32_e32 v19, 1.0, v19
	v_rcp_f32_e32 v23, v19
	s_nop 0
	v_pk_mul_f32 v[20:21], v[22:23], v[20:21]
	s_nop 0
	v_pk_mul_f32 v[20:21], v[30:31], v[20:21]
	s_nop 0
	v_cvt_pk_bf16_f32 v19, v20, v21
	v_mov_b32_e32 v102, v18
	v_mov_b32_e32 v103, v19
	s_nop 1
	v_permlane32_swap_b32_e32 v100, v102
	v_permlane32_swap_b32_e32 v101, v103
	s_nop 1
	global_store_dwordx4 v[104:105], v[100:103], off offset:32 sc1
	s_waitcnt vmcnt(5)
	v_lshlrev_b32_e32 v18, 16, v38
	v_and_b32_e32 v19, 0xffff0000, v38
	v_mul_f32_e32 v20, 0xbfb8aa3b, v18
	v_mul_f32_e32 v21, 0xbfb8aa3b, v19
	v_exp_f32_e32 v20, v20
	v_exp_f32_e32 v21, v21
	v_add_f32_e32 v20, 1.0, v20
	v_add_f32_e32 v21, 1.0, v21
	v_rcp_f32_e32 v20, v20
	v_rcp_f32_e32 v21, v21
	s_nop 0
	v_pk_mul_f32 v[18:19], v[20:21], v[18:19]
	s_nop 0
	v_pk_mul_f32 v[0:1], v[0:1], v[18:19]
	v_lshlrev_b32_e32 v18, 16, v39
	v_cvt_pk_bf16_f32 v0, v0, v1
	v_mul_f32_e32 v1, 0xbfb8aa3b, v18
	v_exp_f32_e32 v1, v1
	v_and_b32_e32 v19, 0xffff0000, v39
	v_add_f32_e32 v1, 1.0, v1
	v_rcp_f32_e32 v20, v1
	v_mul_f32_e32 v1, 0xbfb8aa3b, v19
	v_exp_f32_e32 v1, v1
	s_nop 0
	v_add_f32_e32 v1, 1.0, v1
	v_rcp_f32_e32 v21, v1
	s_nop 0
	v_pk_mul_f32 v[18:19], v[20:21], v[18:19]
	s_nop 0
	v_pk_mul_f32 v[2:3], v[2:3], v[18:19]
	s_nop 0
	v_cvt_pk_bf16_f32 v1, v2, v3
	v_mov_b32_e32 v100, v0
	v_mov_b32_e32 v101, v1
	s_waitcnt vmcnt(4)
	v_lshlrev_b32_e32 v0, 16, v36
	v_and_b32_e32 v1, 0xffff0000, v36
	v_mul_f32_e32 v2, 0xbfb8aa3b, v0
	v_mul_f32_e32 v3, 0xbfb8aa3b, v1
	v_exp_f32_e32 v2, v2
	v_exp_f32_e32 v3, v3
	v_add_f32_e32 v2, 1.0, v2
	v_add_f32_e32 v3, 1.0, v3
	v_rcp_f32_e32 v2, v2
	v_rcp_f32_e32 v3, v3
	s_nop 0
	v_pk_mul_f32 v[0:1], v[2:3], v[0:1]
	s_nop 0
	v_pk_mul_f32 v[0:1], v[4:5], v[0:1]
	v_lshlrev_b32_e32 v2, 16, v37
	v_cvt_pk_bf16_f32 v0, v0, v1
	v_mul_f32_e32 v1, 0xbfb8aa3b, v2
	v_exp_f32_e32 v1, v1
	v_and_b32_e32 v3, 0xffff0000, v37
	v_add_f32_e32 v1, 1.0, v1
	v_rcp_f32_e32 v4, v1
	v_mul_f32_e32 v1, 0xbfb8aa3b, v3
	v_exp_f32_e32 v1, v1
	s_nop 0
	v_add_f32_e32 v1, 1.0, v1
	v_rcp_f32_e32 v5, v1
	s_nop 0
	v_pk_mul_f32 v[2:3], v[4:5], v[2:3]
	s_nop 0
	v_pk_mul_f32 v[2:3], v[6:7], v[2:3]
	s_nop 0
	v_cvt_pk_bf16_f32 v1, v2, v3
	v_mov_b32_e32 v102, v0
	v_mov_b32_e32 v103, v1
	s_nop 1
	v_permlane32_swap_b32_e32 v100, v102
	v_permlane32_swap_b32_e32 v101, v103
	s_nop 1
	global_store_dwordx4 v[104:105], v[100:103], off offset:64 sc1
	s_waitcnt vmcnt(4)
	v_lshlrev_b32_e32 v0, 16, v34
	v_and_b32_e32 v1, 0xffff0000, v34
	v_mul_f32_e32 v2, 0xbfb8aa3b, v0
	v_mul_f32_e32 v3, 0xbfb8aa3b, v1
	v_exp_f32_e32 v2, v2
	v_exp_f32_e32 v3, v3
	v_add_f32_e32 v2, 1.0, v2
	v_add_f32_e32 v3, 1.0, v3
	v_rcp_f32_e32 v2, v2
	v_rcp_f32_e32 v3, v3
	s_nop 0
	v_pk_mul_f32 v[0:1], v[2:3], v[0:1]
	s_nop 0
	v_pk_mul_f32 v[0:1], v[8:9], v[0:1]
	v_lshlrev_b32_e32 v2, 16, v35
	v_cvt_pk_bf16_f32 v0, v0, v1
	v_mul_f32_e32 v1, 0xbfb8aa3b, v2
	v_exp_f32_e32 v1, v1
	v_and_b32_e32 v3, 0xffff0000, v35
	v_add_f32_e32 v1, 1.0, v1
	v_rcp_f32_e32 v4, v1
	v_mul_f32_e32 v1, 0xbfb8aa3b, v3
	v_exp_f32_e32 v1, v1
	s_nop 0
	v_add_f32_e32 v1, 1.0, v1
	v_rcp_f32_e32 v5, v1
	s_nop 0
	v_pk_mul_f32 v[2:3], v[4:5], v[2:3]
	s_nop 0
	v_pk_mul_f32 v[2:3], v[10:11], v[2:3]
	s_nop 0
	v_cvt_pk_bf16_f32 v1, v2, v3
	v_mov_b32_e32 v100, v0
	v_mov_b32_e32 v101, v1
	s_waitcnt vmcnt(3)
	v_lshlrev_b32_e32 v0, 16, v32
	v_and_b32_e32 v1, 0xffff0000, v32
	v_mul_f32_e32 v2, 0xbfb8aa3b, v0
	v_mul_f32_e32 v3, 0xbfb8aa3b, v1
	v_exp_f32_e32 v2, v2
	v_exp_f32_e32 v3, v3
	v_add_f32_e32 v2, 1.0, v2
	v_add_f32_e32 v3, 1.0, v3
	v_rcp_f32_e32 v2, v2
	v_rcp_f32_e32 v3, v3
	s_nop 0
	v_pk_mul_f32 v[0:1], v[2:3], v[0:1]
	s_nop 0
	v_pk_mul_f32 v[0:1], v[12:13], v[0:1]
	v_lshlrev_b32_e32 v2, 16, v33
	v_cvt_pk_bf16_f32 v0, v0, v1
	v_mul_f32_e32 v1, 0xbfb8aa3b, v2
	v_exp_f32_e32 v1, v1
	v_and_b32_e32 v3, 0xffff0000, v33
	v_add_f32_e32 v1, 1.0, v1
	v_rcp_f32_e32 v4, v1
	v_mul_f32_e32 v1, 0xbfb8aa3b, v3
	v_exp_f32_e32 v1, v1
	s_nop 0
	v_add_f32_e32 v1, 1.0, v1
	v_rcp_f32_e32 v5, v1
	s_nop 0
	v_pk_mul_f32 v[2:3], v[4:5], v[2:3]
	s_nop 0
	v_pk_mul_f32 v[2:3], v[14:15], v[2:3]
	s_nop 0
	v_cvt_pk_bf16_f32 v1, v2, v3
	v_mov_b32_e32 v102, v0
	v_mov_b32_e32 v103, v1
	s_nop 1
	v_permlane32_swap_b32_e32 v100, v102
	v_permlane32_swap_b32_e32 v101, v103
	s_nop 1
	global_store_dwordx4 v[104:105], v[100:103], off offset:96 sc1
